# NSA fast paths: the 16 per-step x*scale-m v_fma_f32 paired into 8 v_pk_fma_f32 (bit-identical, fewer VALU issue slots)
# baseline (speedup 1.0000x reference)
; #define LAS __attribute__((address_space(3)))
; DI float xh_sum(float x) { const unsigned u = __float_as_uint(x); const auto r = __builtin_amdgcn_permlane32_swap(u, u, false, false); return __uint_as_float(r[0]) + __uint_as_float(r[1]); }
; #define MFMA32(a, b, c) __builtin_amdgcn_mfma_f32_32x32x16_bf16((a), (b), (c), 0, 0, 0)
; DI bf16x8 cat44(s16x4 a, s16x4 b) { return __builtin_shufflevector(a, b, 0, 1, 2, 3, 4, 5, 6, 7); }
; template <int MODE>
; DI void co_finish(f32x16 S, LAS unsigned char* st, int key_base, AttnState& as, int tq, bool rowsel, int vb_in, int hh) {
;     ...
;     const float mxs = mx * SM_SCALE; const bool need = mxs > as.m + 8.f;
;     const float mnew = need ? mxs : as.m, muse = -fmaxf(mnew, -1e20f); float ps = 0.f;
; #pragma unroll
;     for (int i = 0; i < 16; ++i) { const float p = __builtin_amdgcn_exp2f(__builtin_fmaf(S[i], SM_SCALE, muse)); S[i] = p; ps += p; }
;     ps = xh_sum(ps);
;     if (__builtin_amdgcn_ballot_w64(need) != 0ull) {
;         const float alpha = __builtin_amdgcn_exp2f(as.m - mnew);
;         as.l *= alpha;
; #pragma unroll
;         for (int dt = 0; dt < 4; ++dt)
; #pragma unroll
;             for (int i = 0; i < 16; ++i) as.acc[dt][i] *= alpha;
;     }
;     as.l += ps; as.m = mnew;
;     const bf16x8 p0 = pack8(S, 0), p1 = pack8(S, 1);
;     __builtin_amdgcn_s_setprio(1);
; #pragma unroll
;     for (int dt = 0; dt < 4; ++dt) {
;         LAS unsigned char* vp = st + 2048 * dt;
;         const bf16x8 a0 = cat44(*(const LAS s16x4*)(vp + (vb ^ 0)), *(const LAS s16x4*)(vp + (vb ^ 16))), a1 = cat44(*(const LAS s16x4*)(vp + (vb ^ 32)), *(const LAS s16x4*)(vp + (vb ^ 48)));
;         as.acc[dt] = MFMA32(a0, p0, as.acc[dt]); as.acc[dt] = MFMA32(a1, p1, as.acc[dt]);
;     }
.Lfast_sel_nr:
	v_pk_fma_f32 v[16:17], v[16:17], s[52:53], v[14:15] op_sel_hi:[1,0,0] neg_lo:[0,0,1] neg_hi:[0,0,1]
	v_exp_f32_e32 v16, v16
	v_exp_f32_e32 v17, v17
	v_add_f32_e32 v10, 0, v16
	v_add_f32_e32 v10, v17, v10
	s_waitcnt lgkmcnt(12)
	v_mfma_f32_32x32x16_bf16 v[96:111], v[228:231], v[124:127], v[96:111]
	v_pk_fma_f32 v[18:19], v[18:19], s[52:53], v[14:15] op_sel_hi:[1,0,0] neg_lo:[0,0,1] neg_hi:[0,0,1]
	v_exp_f32_e32 v18, v18
	v_exp_f32_e32 v19, v19
	v_add_f32_e32 v10, v18, v10
	v_add_f32_e32 v10, v19, v10
	s_waitcnt lgkmcnt(11)
	v_mfma_f32_32x32x16_bf16 v[96:111], v[232:235], v[128:131], v[96:111]
	v_pk_fma_f32 v[20:21], v[20:21], s[52:53], v[14:15] op_sel_hi:[1,0,0] neg_lo:[0,0,1] neg_hi:[0,0,1]
	v_exp_f32_e32 v20, v20
	v_exp_f32_e32 v21, v21
	v_add_f32_e32 v10, v20, v10
	v_add_f32_e32 v10, v21, v10
	s_waitcnt lgkmcnt(10)
	v_mfma_f32_32x32x16_bf16 v[96:111], v[240:243], v[132:135], v[96:111]
	v_pk_fma_f32 v[22:23], v[22:23], s[52:53], v[14:15] op_sel_hi:[1,0,0] neg_lo:[0,0,1] neg_hi:[0,0,1]
	v_exp_f32_e32 v22, v22
	v_exp_f32_e32 v23, v23
	v_add_f32_e32 v10, v22, v10
	v_add_f32_e32 v10, v23, v10
	v_cvt_pk_bf16_f32 v2, v16, v17
	v_cvt_pk_bf16_f32 v3, v18, v19
	v_cvt_pk_bf16_f32 v4, v20, v21
	v_cvt_pk_bf16_f32 v5, v22, v23
	s_waitcnt lgkmcnt(9)
	v_mfma_f32_32x32x16_bf16 v[96:111], v[244:247], v[136:139], v[96:111]
	s_waitcnt lgkmcnt(4)
	v_mfma_f32_32x32x16_bf16 v[64:79], v[184:187], v[2:5], v[64:79]
	v_pk_fma_f32 v[24:25], v[24:25], s[52:53], v[14:15] op_sel_hi:[1,0,0] neg_lo:[0,0,1] neg_hi:[0,0,1]
	v_exp_f32_e32 v24, v24
	v_exp_f32_e32 v25, v25
	v_add_f32_e32 v10, v24, v10
	v_add_f32_e32 v10, v25, v10
	v_mfma_f32_32x32x16_bf16 v[96:111], v[248:251], v[140:143], v[96:111]
	v_mfma_f32_32x32x16_bf16 v[80:95], v[180:183], v[2:5], v[80:95]
	ds_read_b64 v[198:199], v255 offset:8192
	ds_read_b64 v[200:201], v214 offset:8192
	ds_read_b64 v[202:203], v255 offset:10240
	ds_read_b64 v[204:205], v214 offset:10240
	ds_read_b64 v[206:207], v255 offset:12288
	ds_read_b64 v[208:209], v214 offset:12288
	ds_read_b64 v[210:211], v255 offset:14336
	ds_read_b64 v[212:213], v214 offset:14336
	v_pk_fma_f32 v[26:27], v[26:27], s[52:53], v[14:15] op_sel_hi:[1,0,0] neg_lo:[0,0,1] neg_hi:[0,0,1]
	v_exp_f32_e32 v26, v26
	v_exp_f32_e32 v27, v27
	v_add_f32_e32 v10, v26, v10
	v_add_f32_e32 v10, v27, v10
	s_waitcnt lgkmcnt(10)
	v_mfma_f32_32x32x16_bf16 v[48:63], v[188:191], v[2:5], v[48:63]
	v_pk_fma_f32 v[28:29], v[28:29], s[52:53], v[14:15] op_sel_hi:[1,0,0] neg_lo:[0,0,1] neg_hi:[0,0,1]
	v_exp_f32_e32 v28, v28
	v_exp_f32_e32 v29, v29
	v_add_f32_e32 v10, v28, v10
	v_add_f32_e32 v10, v29, v10
	s_waitcnt lgkmcnt(8)
	v_mfma_f32_32x32x16_bf16 v[32:47], v[192:195], v[2:5], v[32:47]
	v_pk_fma_f32 v[30:31], v[30:31], s[52:53], v[14:15] op_sel_hi:[1,0,0] neg_lo:[0,0,1] neg_hi:[0,0,1]
	v_exp_f32_e32 v30, v30
	v_exp_f32_e32 v31, v31
	v_add_f32_e32 v10, v30, v10
	v_add_f32_e32 v10, v31, v10
	v_mov_b32_e32 v11, v10
	v_cvt_pk_bf16_f32 v6, v24, v25
	v_cvt_pk_bf16_f32 v7, v26, v27
	v_cvt_pk_bf16_f32 v8, v28, v29
	v_cvt_pk_bf16_f32 v9, v30, v31
	v_permlane32_swap_b32_e32 v10, v11
	v_add_f32_e32 v10, v10, v11
	v_add_f32_e32 v163, v10, v163
	s_waitcnt lgkmcnt(4)
	v_mfma_f32_32x32x16_bf16 v[64:79], v[202:205], v[6:9], v[64:79]
	v_mfma_f32_32x32x16_bf16 v[80:95], v[198:201], v[6:9], v[80:95]
	s_waitcnt lgkmcnt(2)
	v_mfma_f32_32x32x16_bf16 v[48:63], v[206:209], v[6:9], v[48:63]
	s_waitcnt lgkmcnt(0)
	v_mfma_f32_32x32x16_bf16 v[32:47], v[210:213], v[6:9], v[32:47]
	s_branch .LBB0_553

; #define LAS __attribute__((address_space(3)))
; DI float xh_sum(float x) { const unsigned u = __float_as_uint(x); const auto r = __builtin_amdgcn_permlane32_swap(u, u, false, false); return __uint_as_float(r[0]) + __uint_as_float(r[1]); }
; #define MFMA32(a, b, c) __builtin_amdgcn_mfma_f32_32x32x16_bf16((a), (b), (c), 0, 0, 0)
; DI bf16x8 cat44(s16x4 a, s16x4 b) { return __builtin_shufflevector(a, b, 0, 1, 2, 3, 4, 5, 6, 7); }
; template <int MODE>
; DI void co_finish(f32x16 S, LAS unsigned char* st, int key_base, AttnState& as, int tq, bool rowsel, int vb_in, int hh) {
;     ...
;     const float mxs = mx * SM_SCALE; const bool need = mxs > as.m + 8.f;
;     const float mnew = need ? mxs : as.m, muse = -fmaxf(mnew, -1e20f); float ps = 0.f;
; #pragma unroll
;     for (int i = 0; i < 16; ++i) { const float p = __builtin_amdgcn_exp2f(__builtin_fmaf(S[i], SM_SCALE, muse)); S[i] = p; ps += p; }
;     ps = xh_sum(ps);
;     if (__builtin_amdgcn_ballot_w64(need) != 0ull) {
;         const float alpha = __builtin_amdgcn_exp2f(as.m - mnew);
;         as.l *= alpha;
; #pragma unroll
;         for (int dt = 0; dt < 4; ++dt)
; #pragma unroll
;             for (int i = 0; i < 16; ++i) as.acc[dt][i] *= alpha;
;     }
;     as.l += ps; as.m = mnew;
;     const bf16x8 p0 = pack8(S, 0), p1 = pack8(S, 1);
;     __builtin_amdgcn_s_setprio(1);
; #pragma unroll
;     for (int dt = 0; dt < 4; ++dt) {
;         LAS unsigned char* vp = st + 2048 * dt;
;         const bf16x8 a0 = cat44(*(const LAS s16x4*)(vp + (vb ^ 0)), *(const LAS s16x4*)(vp + (vb ^ 16))), a1 = cat44(*(const LAS s16x4*)(vp + (vb ^ 32)), *(const LAS s16x4*)(vp + (vb ^ 48)));
;         as.acc[dt] = MFMA32(a0, p0, as.acc[dt]); as.acc[dt] = MFMA32(a1, p1, as.acc[dt]);
;     }
.Lfast_win_nr:
	v_pk_fma_f32 v[16:17], v[16:17], s[52:53], v[14:15] op_sel_hi:[1,0,0] neg_lo:[0,0,1] neg_hi:[0,0,1]
	v_exp_f32_e32 v16, v16
	v_exp_f32_e32 v17, v17
	v_add_f32_e32 v10, 0, v16
	v_add_f32_e32 v10, v17, v10
	s_waitcnt lgkmcnt(12)
	v_mfma_f32_32x32x16_bf16 v[96:111], v[228:231], v[124:127], v[96:111]
	v_pk_fma_f32 v[18:19], v[18:19], s[52:53], v[14:15] op_sel_hi:[1,0,0] neg_lo:[0,0,1] neg_hi:[0,0,1]
	v_exp_f32_e32 v18, v18
	v_exp_f32_e32 v19, v19
	v_add_f32_e32 v10, v18, v10
	v_add_f32_e32 v10, v19, v10
	s_waitcnt lgkmcnt(11)
	v_mfma_f32_32x32x16_bf16 v[96:111], v[232:235], v[128:131], v[96:111]
	v_pk_fma_f32 v[20:21], v[20:21], s[52:53], v[14:15] op_sel_hi:[1,0,0] neg_lo:[0,0,1] neg_hi:[0,0,1]
	v_exp_f32_e32 v20, v20
	v_exp_f32_e32 v21, v21
	v_add_f32_e32 v10, v20, v10
	v_add_f32_e32 v10, v21, v10
	s_waitcnt lgkmcnt(10)
	v_mfma_f32_32x32x16_bf16 v[96:111], v[240:243], v[132:135], v[96:111]
	v_pk_fma_f32 v[22:23], v[22:23], s[52:53], v[14:15] op_sel_hi:[1,0,0] neg_lo:[0,0,1] neg_hi:[0,0,1]
	v_exp_f32_e32 v22, v22
	v_exp_f32_e32 v23, v23
	v_add_f32_e32 v10, v22, v10
	v_add_f32_e32 v10, v23, v10
	v_cvt_pk_bf16_f32 v2, v16, v17
	v_cvt_pk_bf16_f32 v3, v18, v19
	v_cvt_pk_bf16_f32 v4, v20, v21
	v_cvt_pk_bf16_f32 v5, v22, v23
	s_waitcnt lgkmcnt(9)
	v_mfma_f32_32x32x16_bf16 v[96:111], v[244:247], v[136:139], v[96:111]
	s_waitcnt lgkmcnt(4)
	v_mfma_f32_32x32x16_bf16 v[64:79], v[184:187], v[2:5], v[64:79]
	v_pk_fma_f32 v[24:25], v[24:25], s[52:53], v[14:15] op_sel_hi:[1,0,0] neg_lo:[0,0,1] neg_hi:[0,0,1]
	v_exp_f32_e32 v24, v24
	v_exp_f32_e32 v25, v25
	v_add_f32_e32 v10, v24, v10
	v_add_f32_e32 v10, v25, v10
	v_mfma_f32_32x32x16_bf16 v[96:111], v[248:251], v[140:143], v[96:111]
	v_mfma_f32_32x32x16_bf16 v[80:95], v[180:183], v[2:5], v[80:95]
	ds_read_b64 v[198:199], v255 offset:8192
	ds_read_b64 v[200:201], v214 offset:8192
	ds_read_b64 v[202:203], v255 offset:10240
	ds_read_b64 v[204:205], v214 offset:10240
	ds_read_b64 v[206:207], v255 offset:12288
	ds_read_b64 v[208:209], v214 offset:12288
	ds_read_b64 v[210:211], v255 offset:14336
	ds_read_b64 v[212:213], v214 offset:14336
	v_pk_fma_f32 v[26:27], v[26:27], s[52:53], v[14:15] op_sel_hi:[1,0,0] neg_lo:[0,0,1] neg_hi:[0,0,1]
	v_exp_f32_e32 v26, v26
	v_exp_f32_e32 v27, v27
	v_add_f32_e32 v10, v26, v10
	v_add_f32_e32 v10, v27, v10
	s_waitcnt lgkmcnt(10)
	v_mfma_f32_32x32x16_bf16 v[48:63], v[188:191], v[2:5], v[48:63]
	v_pk_fma_f32 v[28:29], v[28:29], s[52:53], v[14:15] op_sel_hi:[1,0,0] neg_lo:[0,0,1] neg_hi:[0,0,1]
	v_exp_f32_e32 v28, v28
	v_exp_f32_e32 v29, v29
	v_add_f32_e32 v10, v28, v10
	v_add_f32_e32 v10, v29, v10
	s_waitcnt lgkmcnt(8)
	v_mfma_f32_32x32x16_bf16 v[32:47], v[192:195], v[2:5], v[32:47]
	v_pk_fma_f32 v[30:31], v[30:31], s[52:53], v[14:15] op_sel_hi:[1,0,0] neg_lo:[0,0,1] neg_hi:[0,0,1]
	v_exp_f32_e32 v30, v30
	v_exp_f32_e32 v31, v31
	v_add_f32_e32 v10, v30, v10
	v_add_f32_e32 v10, v31, v10
	v_mov_b32_e32 v11, v10
	v_cvt_pk_bf16_f32 v6, v24, v25
	v_cvt_pk_bf16_f32 v7, v26, v27
	v_cvt_pk_bf16_f32 v8, v28, v29
	v_cvt_pk_bf16_f32 v9, v30, v31
	v_permlane32_swap_b32_e32 v10, v11
	v_add_f32_e32 v10, v10, v11
	v_add_f32_e32 v175, v10, v175
	s_waitcnt lgkmcnt(4)
	v_mfma_f32_32x32x16_bf16 v[64:79], v[202:205], v[6:9], v[64:79]
	v_mfma_f32_32x32x16_bf16 v[80:95], v[198:201], v[6:9], v[80:95]
	s_waitcnt lgkmcnt(2)
	v_mfma_f32_32x32x16_bf16 v[48:63], v[206:209], v[6:9], v[48:63]
	s_waitcnt lgkmcnt(0)
	v_mfma_f32_32x32x16_bf16 v[32:47], v[210:213], v[6:9], v[32:47]
	s_branch .LBB0_522

; #define LAS __attribute__((address_space(3)))
; DI float xh_sum(float x) { const unsigned u = __float_as_uint(x); const auto r = __builtin_amdgcn_permlane32_swap(u, u, false, false); return __uint_as_float(r[0]) + __uint_as_float(r[1]); }
; #define MFMA32(a, b, c) __builtin_amdgcn_mfma_f32_32x32x16_bf16((a), (b), (c), 0, 0, 0)
; DI bf16x8 cat44(s16x4 a, s16x4 b) { return __builtin_shufflevector(a, b, 0, 1, 2, 3, 4, 5, 6, 7); }
; template <int MODE>
; DI void co_finish(f32x16 S, LAS unsigned char* st, int key_base, AttnState& as, int tq, bool rowsel, int vb_in, int hh) {
;     ...
;     const float mxs = mx * SM_SCALE; const bool need = mxs > as.m + 8.f;
;     const float mnew = need ? mxs : as.m, muse = -fmaxf(mnew, -1e20f); float ps = 0.f;
; #pragma unroll
;     for (int i = 0; i < 16; ++i) { const float p = __builtin_amdgcn_exp2f(__builtin_fmaf(S[i], SM_SCALE, muse)); S[i] = p; ps += p; }
;     ps = xh_sum(ps);
;     if (__builtin_amdgcn_ballot_w64(need) != 0ull) {
;         const float alpha = __builtin_amdgcn_exp2f(as.m - mnew);
;         as.l *= alpha;
; #pragma unroll
;         for (int dt = 0; dt < 4; ++dt)
; #pragma unroll
;             for (int i = 0; i < 16; ++i) as.acc[dt][i] *= alpha;
;     }
;     as.l += ps; as.m = mnew;
;     const bf16x8 p0 = pack8(S, 0), p1 = pack8(S, 1);
;     __builtin_amdgcn_s_setprio(1);
; #pragma unroll
;     for (int dt = 0; dt < 4; ++dt) {
;         LAS unsigned char* vp = st + 2048 * dt;
;         const bf16x8 a0 = cat44(*(const LAS s16x4*)(vp + (vb ^ 0)), *(const LAS s16x4*)(vp + (vb ^ 16))), a1 = cat44(*(const LAS s16x4*)(vp + (vb ^ 32)), *(const LAS s16x4*)(vp + (vb ^ 48)));
;         as.acc[dt] = MFMA32(a0, p0, as.acc[dt]); as.acc[dt] = MFMA32(a1, p1, as.acc[dt]);
;     }
.Lfastf_sel_nr:
	v_pk_fma_f32 v[16:17], v[16:17], s[52:53], v[14:15] op_sel_hi:[1,0,0] neg_lo:[0,0,1] neg_hi:[0,0,1]
	v_exp_f32_e32 v16, v16
	v_exp_f32_e32 v17, v17
	v_add_f32_e32 v10, 0, v16
	v_add_f32_e32 v10, v17, v10
	v_pk_fma_f32 v[18:19], v[18:19], s[52:53], v[14:15] op_sel_hi:[1,0,0] neg_lo:[0,0,1] neg_hi:[0,0,1]
	v_exp_f32_e32 v18, v18
	v_exp_f32_e32 v19, v19
	v_add_f32_e32 v10, v18, v10
	v_add_f32_e32 v10, v19, v10
	v_pk_fma_f32 v[20:21], v[20:21], s[52:53], v[14:15] op_sel_hi:[1,0,0] neg_lo:[0,0,1] neg_hi:[0,0,1]
	v_exp_f32_e32 v20, v20
	v_exp_f32_e32 v21, v21
	v_add_f32_e32 v10, v20, v10
	v_add_f32_e32 v10, v21, v10
	v_pk_fma_f32 v[22:23], v[22:23], s[52:53], v[14:15] op_sel_hi:[1,0,0] neg_lo:[0,0,1] neg_hi:[0,0,1]
	v_exp_f32_e32 v22, v22
	v_exp_f32_e32 v23, v23
	v_add_f32_e32 v10, v22, v10
	v_add_f32_e32 v10, v23, v10
	v_cvt_pk_bf16_f32 v2, v16, v17
	v_cvt_pk_bf16_f32 v3, v18, v19
	v_cvt_pk_bf16_f32 v4, v20, v21
	v_cvt_pk_bf16_f32 v5, v22, v23
	s_nop 1
	s_waitcnt lgkmcnt(4)
	v_mfma_f32_32x32x16_bf16 v[64:79], v[184:187], v[2:5], v[64:79]
	v_pk_fma_f32 v[24:25], v[24:25], s[52:53], v[14:15] op_sel_hi:[1,0,0] neg_lo:[0,0,1] neg_hi:[0,0,1]
	v_exp_f32_e32 v24, v24
	v_exp_f32_e32 v25, v25
	v_add_f32_e32 v10, v24, v10
	v_add_f32_e32 v10, v25, v10
	v_mfma_f32_32x32x16_bf16 v[80:95], v[180:183], v[2:5], v[80:95]
	ds_read_b64 v[198:199], v255 offset:8192
	ds_read_b64 v[200:201], v214 offset:8192
	ds_read_b64 v[202:203], v255 offset:10240
	ds_read_b64 v[204:205], v214 offset:10240
	ds_read_b64 v[206:207], v255 offset:12288
	ds_read_b64 v[208:209], v214 offset:12288
	ds_read_b64 v[210:211], v255 offset:14336
	ds_read_b64 v[212:213], v214 offset:14336
	v_pk_fma_f32 v[26:27], v[26:27], s[52:53], v[14:15] op_sel_hi:[1,0,0] neg_lo:[0,0,1] neg_hi:[0,0,1]
	v_exp_f32_e32 v26, v26
	v_exp_f32_e32 v27, v27
	v_add_f32_e32 v10, v26, v10
	v_add_f32_e32 v10, v27, v10
	s_waitcnt lgkmcnt(10)
	v_mfma_f32_32x32x16_bf16 v[48:63], v[188:191], v[2:5], v[48:63]
	v_pk_fma_f32 v[28:29], v[28:29], s[52:53], v[14:15] op_sel_hi:[1,0,0] neg_lo:[0,0,1] neg_hi:[0,0,1]
	v_exp_f32_e32 v28, v28
	v_exp_f32_e32 v29, v29
	v_add_f32_e32 v10, v28, v10
	v_add_f32_e32 v10, v29, v10
	s_waitcnt lgkmcnt(8)
	v_mfma_f32_32x32x16_bf16 v[32:47], v[192:195], v[2:5], v[32:47]
	v_pk_fma_f32 v[30:31], v[30:31], s[52:53], v[14:15] op_sel_hi:[1,0,0] neg_lo:[0,0,1] neg_hi:[0,0,1]
	v_exp_f32_e32 v30, v30
	v_exp_f32_e32 v31, v31
	v_add_f32_e32 v10, v30, v10
	v_add_f32_e32 v10, v31, v10
	v_mov_b32_e32 v11, v10
	v_cvt_pk_bf16_f32 v6, v24, v25
	v_cvt_pk_bf16_f32 v7, v26, v27
	v_cvt_pk_bf16_f32 v8, v28, v29
	v_cvt_pk_bf16_f32 v9, v30, v31
	v_permlane32_swap_b32_e32 v10, v11
	v_add_f32_e32 v10, v10, v11
	v_add_f32_e32 v163, v10, v163
	s_waitcnt lgkmcnt(4)
	v_mfma_f32_32x32x16_bf16 v[64:79], v[202:205], v[6:9], v[64:79]
	v_mfma_f32_32x32x16_bf16 v[80:95], v[198:201], v[6:9], v[80:95]
	s_waitcnt lgkmcnt(2)
	v_mfma_f32_32x32x16_bf16 v[48:63], v[206:209], v[6:9], v[48:63]
	s_waitcnt lgkmcnt(0)
	v_mfma_f32_32x32x16_bf16 v[32:47], v[210:213], v[6:9], v[32:47]
	s_branch .LBB0_553

; #define LAS __attribute__((address_space(3)))
; DI float xh_sum(float x) { const unsigned u = __float_as_uint(x); const auto r = __builtin_amdgcn_permlane32_swap(u, u, false, false); return __uint_as_float(r[0]) + __uint_as_float(r[1]); }
; #define MFMA32(a, b, c) __builtin_amdgcn_mfma_f32_32x32x16_bf16((a), (b), (c), 0, 0, 0)
; DI bf16x8 cat44(s16x4 a, s16x4 b) { return __builtin_shufflevector(a, b, 0, 1, 2, 3, 4, 5, 6, 7); }
; template <int MODE>
; DI void co_finish(f32x16 S, LAS unsigned char* st, int key_base, AttnState& as, int tq, bool rowsel, int vb_in, int hh) {
;     ...
;     const float mxs = mx * SM_SCALE; const bool need = mxs > as.m + 8.f;
;     const float mnew = need ? mxs : as.m, muse = -fmaxf(mnew, -1e20f); float ps = 0.f;
; #pragma unroll
;     for (int i = 0; i < 16; ++i) { const float p = __builtin_amdgcn_exp2f(__builtin_fmaf(S[i], SM_SCALE, muse)); S[i] = p; ps += p; }
;     ps = xh_sum(ps);
;     if (__builtin_amdgcn_ballot_w64(need) != 0ull) {
;         const float alpha = __builtin_amdgcn_exp2f(as.m - mnew);
;         as.l *= alpha;
; #pragma unroll
;         for (int dt = 0; dt < 4; ++dt)
; #pragma unroll
;             for (int i = 0; i < 16; ++i) as.acc[dt][i] *= alpha;
;     }
;     as.l += ps; as.m = mnew;
;     const bf16x8 p0 = pack8(S, 0), p1 = pack8(S, 1);
;     __builtin_amdgcn_s_setprio(1);
; #pragma unroll
;     for (int dt = 0; dt < 4; ++dt) {
;         LAS unsigned char* vp = st + 2048 * dt;
;         const bf16x8 a0 = cat44(*(const LAS s16x4*)(vp + (vb ^ 0)), *(const LAS s16x4*)(vp + (vb ^ 16))), a1 = cat44(*(const LAS s16x4*)(vp + (vb ^ 32)), *(const LAS s16x4*)(vp + (vb ^ 48)));
;         as.acc[dt] = MFMA32(a0, p0, as.acc[dt]); as.acc[dt] = MFMA32(a1, p1, as.acc[dt]);
;     }
.Lfastf_win_nr:
	v_pk_fma_f32 v[16:17], v[16:17], s[52:53], v[14:15] op_sel_hi:[1,0,0] neg_lo:[0,0,1] neg_hi:[0,0,1]
	v_exp_f32_e32 v16, v16
	v_exp_f32_e32 v17, v17
	v_add_f32_e32 v10, 0, v16
	v_add_f32_e32 v10, v17, v10
	v_pk_fma_f32 v[18:19], v[18:19], s[52:53], v[14:15] op_sel_hi:[1,0,0] neg_lo:[0,0,1] neg_hi:[0,0,1]
	v_exp_f32_e32 v18, v18
	v_exp_f32_e32 v19, v19
	v_add_f32_e32 v10, v18, v10
	v_add_f32_e32 v10, v19, v10
	v_pk_fma_f32 v[20:21], v[20:21], s[52:53], v[14:15] op_sel_hi:[1,0,0] neg_lo:[0,0,1] neg_hi:[0,0,1]
	v_exp_f32_e32 v20, v20
	v_exp_f32_e32 v21, v21
	v_add_f32_e32 v10, v20, v10
	v_add_f32_e32 v10, v21, v10
	v_pk_fma_f32 v[22:23], v[22:23], s[52:53], v[14:15] op_sel_hi:[1,0,0] neg_lo:[0,0,1] neg_hi:[0,0,1]
	v_exp_f32_e32 v22, v22
	v_exp_f32_e32 v23, v23
	v_add_f32_e32 v10, v22, v10
	v_add_f32_e32 v10, v23, v10
	v_cvt_pk_bf16_f32 v2, v16, v17
	v_cvt_pk_bf16_f32 v3, v18, v19
	v_cvt_pk_bf16_f32 v4, v20, v21
	v_cvt_pk_bf16_f32 v5, v22, v23
	s_nop 1
	s_waitcnt lgkmcnt(4)
	v_mfma_f32_32x32x16_bf16 v[64:79], v[184:187], v[2:5], v[64:79]
	v_pk_fma_f32 v[24:25], v[24:25], s[52:53], v[14:15] op_sel_hi:[1,0,0] neg_lo:[0,0,1] neg_hi:[0,0,1]
	v_exp_f32_e32 v24, v24
	v_exp_f32_e32 v25, v25
	v_add_f32_e32 v10, v24, v10
	v_add_f32_e32 v10, v25, v10
	v_mfma_f32_32x32x16_bf16 v[80:95], v[180:183], v[2:5], v[80:95]
	ds_read_b64 v[198:199], v255 offset:8192
	ds_read_b64 v[200:201], v214 offset:8192
	ds_read_b64 v[202:203], v255 offset:10240
	ds_read_b64 v[204:205], v214 offset:10240
	ds_read_b64 v[206:207], v255 offset:12288
	ds_read_b64 v[208:209], v214 offset:12288
	ds_read_b64 v[210:211], v255 offset:14336
	ds_read_b64 v[212:213], v214 offset:14336
	v_pk_fma_f32 v[26:27], v[26:27], s[52:53], v[14:15] op_sel_hi:[1,0,0] neg_lo:[0,0,1] neg_hi:[0,0,1]
	v_exp_f32_e32 v26, v26
	v_exp_f32_e32 v27, v27
	v_add_f32_e32 v10, v26, v10
	v_add_f32_e32 v10, v27, v10
	s_waitcnt lgkmcnt(10)
	v_mfma_f32_32x32x16_bf16 v[48:63], v[188:191], v[2:5], v[48:63]
	v_pk_fma_f32 v[28:29], v[28:29], s[52:53], v[14:15] op_sel_hi:[1,0,0] neg_lo:[0,0,1] neg_hi:[0,0,1]
	v_exp_f32_e32 v28, v28
	v_exp_f32_e32 v29, v29
	v_add_f32_e32 v10, v28, v10
	v_add_f32_e32 v10, v29, v10
	s_waitcnt lgkmcnt(8)
	v_mfma_f32_32x32x16_bf16 v[32:47], v[192:195], v[2:5], v[32:47]
	v_pk_fma_f32 v[30:31], v[30:31], s[52:53], v[14:15] op_sel_hi:[1,0,0] neg_lo:[0,0,1] neg_hi:[0,0,1]
	v_exp_f32_e32 v30, v30
	v_exp_f32_e32 v31, v31
	v_add_f32_e32 v10, v30, v10
	v_add_f32_e32 v10, v31, v10
	v_mov_b32_e32 v11, v10
	v_cvt_pk_bf16_f32 v6, v24, v25
	v_cvt_pk_bf16_f32 v7, v26, v27
	v_cvt_pk_bf16_f32 v8, v28, v29
	v_cvt_pk_bf16_f32 v9, v30, v31
	v_permlane32_swap_b32_e32 v10, v11
	v_add_f32_e32 v10, v10, v11
	v_add_f32_e32 v175, v10, v175
	s_waitcnt lgkmcnt(4)
	v_mfma_f32_32x32x16_bf16 v[64:79], v[202:205], v[6:9], v[64:79]
	v_mfma_f32_32x32x16_bf16 v[80:95], v[198:201], v[6:9], v[80:95]
	s_waitcnt lgkmcnt(2)
	v_mfma_f32_32x32x16_bf16 v[48:63], v[206:209], v[6:9], v[48:63]
	s_waitcnt lgkmcnt(0)
	v_mfma_f32_32x32x16_bf16 v[32:47], v[210:213], v[6:9], v[32:47]
	s_branch .LBB0_523
